# windowed + neighbourhood attention softmax: masked probabilities zeroed by clamping the exponent's running max at the mask threshold instead of a compare+select per element (104 selects removed); on t
# speedup vs baseline: 1.0030x; 1.0030x over previous
; #define MFMA32(a, b, c) __builtin_amdgcn_mfma_f32_32x32x16_bf16((a), (b), (c), 0, 0, 0)
; DI float fexp2(float x) { return __builtin_amdgcn_exp2f(x); }
; template <int DK, int DV, int MODE, int QB, bool PACK = false>
; DI void attn_item(const AttArgs& a, int q0, int t_lo, int t_hi) {
;     ...
;         const float mc = -m[qb] * cexp;
;         const f32x2 c2 = {cexp, cexp}, mc2 = {mc, mc};
;         f32x2 ps2 = {0.f, 0.f};
; #pragma unroll
;         for (int kb = 0; kb < 2; ++kb)
; #pragma unroll
;           for (int i = 0; i < 16; i += 2) {
;             const f32x2 sv = {s[qb][kb][i], s[qb][kb][i + 1]};
;             const f32x2 e2 = sv * c2 + mc2;
;             f32x2 pv = {fexp2(e2[0]), fexp2(e2[1])};
;             if constexpr (MODE == 1 || MODE == 2) {
;               pv[0] = (sv[0] > -1e29f) ? pv[0] : 0.f;
;               pv[1] = (sv[1] > -1e29f) ? pv[1] : 0.f;
;             }
;             s[qb][kb][i] = pv[0];
;             s[qb][kb][i + 1] = pv[1];
;             ps2 += pv;
;           }
;         lsum[qb] += ps2[0] + ps2[1];
;       }
; #pragma unroll
;       for (int qb = 0; qb < QB; ++qb)
; #pragma unroll
;         for (int kb = 0; kb < 2; ++kb)
; #pragma unroll
;           for (int st = 0; st < 2; ++st) {
;             u32x4 pk;
;             pk[0] = pack2(s[qb][kb][8 * st + 0], s[qb][kb][8 * st + 1]);
;             pk[1] = pack2(s[qb][kb][8 * st + 2], s[qb][kb][8 * st + 3]);
;             pk[2] = pack2(s[qb][kb][8 * st + 4], s[qb][kb][8 * st + 5]);
;             pk[3] = pack2(s[qb][kb][8 * st + 6], s[qb][kb][8 * st + 7]);
;             const bf16x8 pf = __builtin_bit_cast(bf16x8, pk);
;             const unsigned char* vrow = Vb + (kb * 32 + 16 * st + 4 * h + vq) * VST + (16 * vblk + 4 * vp) * 2;
; #pragma unroll
;             for (int d = 0; d < NDB; ++d) {
;               s16x4 lo = __builtin_amdgcn_ds_read_tr16_b64_v4i16((s16x4 __attribute__((address_space(3)))*)(vrow + d * 64));
;               s16x4 hi = __builtin_amdgcn_ds_read_tr16_b64_v4i16((s16x4 __attribute__((address_space(3)))*)(vrow + 8 * VST + d * 64));
;               const bf16x8 vf = __builtin_shufflevector(lo, hi, 0, 1, 2, 3, 4, 5, 6, 7);
;               o[qb][d] = MFMA32(vf, pf, o[qb][d]);
;             }
;           }
.LBB0_746:
	v_max_f32_e32 v84, s17, v187
	v_mul_f32_e32 v84, 0xbfb8aa3b, v84
	s_mov_b32 s46, 0x3fb8aa3b
	v_pk_fma_f32 v[80:81], v[0:1], s[46:47], v[84:85] op_sel_hi:[1,0,0]
	v_exp_f32_e32 v94, v80
	v_exp_f32_e32 v95, v81
	v_readlane_b32 s12, v254, 35
	v_readlane_b32 s14, v254, 37
	v_readlane_b32 s15, v254, 38
	v_readlane_b32 s13, v254, 36
	v_pk_fma_f32 v[80:81], v[4:5], s[46:47], v[84:85] op_sel_hi:[1,0,0]
	v_exp_f32_e32 v124, v80
	v_exp_f32_e32 v125, v81
	v_pk_add_f32 v[0:1], v[94:95], 0 op_sel_hi:[1,0]
	s_mov_b32 s14, s12
	v_pk_fma_f32 v[4:5], v[6:7], s[46:47], v[84:85] op_sel_hi:[1,0,0]
	s_mov_b32 s15, s12
	v_exp_f32_e32 v6, v4
	v_exp_f32_e32 v7, v5
	v_pk_add_f32 v[0:1], v[124:125], v[0:1]
	s_mov_b32 s13, s12
	s_mov_b32 s48, s12
	v_writelane_b32 v254, s48, 35
	v_pk_fma_f32 v[4:5], v[8:9], s[46:47], v[84:85] op_sel_hi:[1,0,0]
	v_exp_f32_e32 v8, v4
	v_exp_f32_e32 v9, v5
	v_pk_add_f32 v[0:1], v[6:7], v[0:1]
	v_cvt_pk_bf16_f32 v6, v6, v7
	v_writelane_b32 v254, s49, 36
	v_writelane_b32 v254, s50, 37
	v_pk_fma_f32 v[4:5], v[10:11], s[46:47], v[84:85] op_sel_hi:[1,0,0]
	v_exp_f32_e32 v80, v4
	v_exp_f32_e32 v81, v5
	v_pk_add_f32 v[0:1], v[8:9], v[0:1]
	v_cvt_pk_bf16_f32 v7, v8, v9
	v_pk_fma_f32 v[10:11], v[100:101], s[46:47], v[84:85] op_sel_hi:[1,0,0]
	v_writelane_b32 v254, s51, 38
	v_pk_fma_f32 v[4:5], v[12:13], s[46:47], v[84:85] op_sel_hi:[1,0,0]
	v_exp_f32_e32 v82, v4
	v_exp_f32_e32 v83, v5
	v_pk_add_f32 v[0:1], v[80:81], v[0:1]
	s_nop 1
	v_pk_fma_f32 v[4:5], v[14:15], s[46:47], v[84:85] op_sel_hi:[1,0,0]
	v_exp_f32_e32 v86, v4
	v_exp_f32_e32 v87, v5
	v_pk_add_f32 v[0:1], v[82:83], v[0:1]
	s_nop 1
	v_pk_fma_f32 v[4:5], v[104:105], s[46:47], v[84:85] op_sel_hi:[1,0,0]
	v_exp_f32_e32 v88, v4
	v_exp_f32_e32 v89, v5
	v_pk_add_f32 v[0:1], v[86:87], v[0:1]
	v_exp_f32_e32 v3, v10
	v_exp_f32_e32 v10, v11
	v_pk_add_f32 v[4:5], v[88:89], v[0:1]
	v_pk_fma_f32 v[0:1], v[106:107], s[46:47], v[84:85] op_sel_hi:[1,0,0]
	v_exp_f32_e32 v0, v0
	v_exp_f32_e32 v1, v1
	s_nop 1
	v_pk_add_f32 v[4:5], v[0:1], v[4:5]
	v_cvt_pk_bf16_f32 v0, v0, v1
	v_mov_b32_e32 v84, v3
	s_nop 1
	v_mov_b32_e32 v85, v10
	v_pk_add_f32 v[4:5], v[84:85], v[4:5]
	v_pk_add_f32 v[4:5], v[4:5], 0 op_sel_hi:[1,0]
	v_cvt_pk_bf16_f32 v1, v84, v85
	v_add_f32_e32 v3, v4, v5
	v_max_f32_e32 v4, s17, v186
	v_mul_f32_e32 v4, 0xbfb8aa3b, v4
	v_pk_fma_f32 v[10:11], v[102:103], s[46:47], v[4:5] op_sel_hi:[1,0,0]
	v_add_f32_e32 v183, v183, v3
	v_exp_f32_e32 v116, v10
	v_exp_f32_e32 v5, v11
	s_nop 0
	v_pk_fma_f32 v[12:13], v[96:97], s[46:47], v[4:5] op_sel_hi:[1,0,0]
	s_nop 0
	v_mov_b32_e32 v117, v5
	v_exp_f32_e32 v118, v12
	v_exp_f32_e32 v5, v13
	v_pk_add_f32 v[10:11], v[116:117], 0 op_sel_hi:[1,0]
	v_pk_fma_f32 v[12:13], v[98:99], s[46:47], v[4:5] op_sel_hi:[1,0,0]
	v_exp_f32_e32 v108, v12
	s_nop 0
	v_mov_b32_e32 v119, v5
	v_exp_f32_e32 v5, v13
	v_pk_add_f32 v[10:11], v[118:119], v[10:11]
	v_pk_fma_f32 v[12:13], v[110:111], s[46:47], v[4:5] op_sel_hi:[1,0,0]
	v_exp_f32_e32 v110, v12
	s_nop 0
	v_mov_b32_e32 v109, v5
	v_exp_f32_e32 v5, v13
	v_pk_add_f32 v[10:11], v[108:109], v[10:11]
	v_pk_fma_f32 v[12:13], v[112:113], s[46:47], v[4:5] op_sel_hi:[1,0,0]
	v_exp_f32_e32 v112, v12
	s_nop 0
	v_mov_b32_e32 v111, v5
	v_exp_f32_e32 v5, v13
	v_pk_add_f32 v[10:11], v[110:111], v[10:11]
	v_pk_fma_f32 v[12:13], v[114:115], s[46:47], v[4:5] op_sel_hi:[1,0,0]
	v_exp_f32_e32 v114, v12
	s_nop 0
	v_mov_b32_e32 v113, v5
	v_exp_f32_e32 v5, v13
	v_pk_add_f32 v[10:11], v[112:113], v[10:11]
	v_pk_fma_f32 v[12:13], v[120:121], s[46:47], v[4:5] op_sel_hi:[1,0,0]
	v_exp_f32_e32 v100, v12
	s_nop 0
	v_mov_b32_e32 v115, v5
	v_exp_f32_e32 v5, v13
	v_pk_add_f32 v[10:11], v[114:115], v[10:11]
	v_pk_fma_f32 v[12:13], v[122:123], s[46:47], v[4:5] op_sel_hi:[1,0,0]
	v_exp_f32_e32 v102, v12
	s_nop 0
	v_mov_b32_e32 v101, v5
	v_exp_f32_e32 v5, v13
	v_pk_add_f32 v[10:11], v[100:101], v[10:11]
	v_pk_fma_f32 v[12:13], v[90:91], s[46:47], v[4:5] op_sel_hi:[1,0,0]
	v_exp_f32_e32 v104, v12
	v_mov_b64_e32 v[122:123], s[14:15]
	v_mov_b32_e32 v103, v5
	v_exp_f32_e32 v105, v13
	v_pk_add_f32 v[10:11], v[102:103], v[10:11]
	v_mov_b64_e32 v[120:121], s[12:13]
	v_cvt_pk_bf16_f32 v90, v80, v81
	v_cvt_pk_bf16_f32 v91, v82, v83
	v_pk_fma_f32 v[4:5], v[92:93], s[46:47], v[4:5] op_sel_hi:[1,0,0]
	v_exp_f32_e32 v106, v4
	v_exp_f32_e32 v107, v5
	v_pk_add_f32 v[10:11], v[104:105], v[10:11]
	v_cvt_pk_bf16_f32 v92, v86, v87
	v_cvt_pk_bf16_f32 v93, v88, v89
	s_nop 0
	v_pk_add_f32 v[4:5], v[106:107], v[10:11]
	s_nop 0
	v_add_f32_e32 v3, v4, v5
	v_cvt_pk_bf16_f32 v4, v94, v95
	v_add3_u32 v94, s33, v181, v184
	ds_read_b64_tr_b16 v[12:13], v94 offset:9216
	ds_read_b64_tr_b16 v[14:15], v94 offset:10368
	ds_read_b64_tr_b16 v[8:9], v94 offset:9280
	ds_read_b64_tr_b16 v[10:11], v94 offset:10432
	v_cvt_pk_bf16_f32 v5, v124, v125
	s_waitcnt lgkmcnt(2)
	v_mfma_f32_32x32x16_bf16 v[32:47], v[12:15], v[120:123], v[32:47]
	ds_read_b64_tr_b16 v[80:81], v94 offset:11520
	ds_read_b64_tr_b16 v[82:83], v94 offset:12672
	v_add_f32_e32 v177, v177, v3
	v_mov_b32_e32 v3, v2
	v_mfma_f32_32x32x16_bf16 v[64:79], v[12:15], v[4:7], v[64:79]
	s_waitcnt lgkmcnt(2)
	v_mfma_f32_32x32x16_bf16 v[48:63], v[8:11], v[4:7], v[48:63]
	ds_read_b64_tr_b16 v[4:5], v94 offset:11584
	ds_read_b64_tr_b16 v[6:7], v94 offset:12736
	v_mfma_f32_32x32x16_bf16 v[16:31], v[8:11], v[120:123], v[16:31]
	v_cvt_pk_bf16_f32 v10, v116, v117
	v_cvt_pk_bf16_f32 v11, v118, v119
	v_mov_b32_e32 v8, v2
	v_mov_b32_e32 v9, v2
	s_waitcnt lgkmcnt(2)
	v_mfma_f32_32x32x16_bf16 v[64:79], v[80:83], v[90:93], v[64:79]
	s_waitcnt lgkmcnt(0)
	v_mfma_f32_32x32x16_bf16 v[48:63], v[4:7], v[90:93], v[48:63]
	ds_read_b64_tr_b16 v[88:89], v94 offset:13824
	ds_read_b64_tr_b16 v[90:91], v94 offset:14976
	ds_read_b64_tr_b16 v[84:85], v94 offset:13888
	ds_read_b64_tr_b16 v[86:87], v94 offset:15040
	ds_read_b64_tr_b16 v[96:97], v94 offset:16128
	ds_read_b64_tr_b16 v[98:99], v94 offset:17280
	ds_read_b64_tr_b16 v[92:93], v94 offset:16192
	ds_read_b64_tr_b16 v[94:95], v94 offset:17344
	v_mfma_f32_32x32x16_bf16 v[32:47], v[80:83], v[8:11], v[32:47]
	v_mfma_f32_32x32x16_bf16 v[16:31], v[4:7], v[8:11], v[16:31]
	v_cvt_pk_bf16_f32 v4, v108, v109
	v_cvt_pk_bf16_f32 v5, v110, v111
	v_cvt_pk_bf16_f32 v6, v112, v113
	v_cvt_pk_bf16_f32 v7, v114, v115
	s_waitcnt lgkmcnt(6)
	v_mfma_f32_32x32x16_bf16 v[64:79], v[88:91], v[0:3], v[64:79]
	s_waitcnt lgkmcnt(4)
	v_mfma_f32_32x32x16_bf16 v[48:63], v[84:87], v[0:3], v[48:63]
	v_mfma_f32_32x32x16_bf16 v[32:47], v[88:91], v[4:7], v[32:47]
	v_mfma_f32_32x32x16_bf16 v[16:31], v[84:87], v[4:7], v[16:31]
	v_cvt_pk_bf16_f32 v4, v100, v101
	v_cvt_pk_bf16_f32 v5, v102, v103
	v_cvt_pk_bf16_f32 v6, v104, v105
	v_cvt_pk_bf16_f32 v7, v106, v107
	s_waitcnt lgkmcnt(2)
	v_mfma_f32_32x32x16_bf16 v[64:79], v[96:99], v[120:123], v[64:79]
	s_waitcnt lgkmcnt(0)
	v_mfma_f32_32x32x16_bf16 v[48:63], v[92:95], v[120:123], v[48:63]
	v_mfma_f32_32x32x16_bf16 v[32:47], v[96:99], v[4:7], v[32:47]
	v_mfma_f32_32x32x16_bf16 v[16:31], v[92:95], v[4:7], v[16:31]

; #define MFMA32(a, b, c) __builtin_amdgcn_mfma_f32_32x32x16_bf16((a), (b), (c), 0, 0, 0)
; DI float fexp2(float x) { return __builtin_amdgcn_exp2f(x); }
; template <int DK, int DV, int MODE, int QB, bool PACK = false>
; DI void attn_item(const AttArgs& a, int q0, int t_lo, int t_hi) {
;     ...
;         const float mc = -m[qb] * cexp;
;         const f32x2 c2 = {cexp, cexp}, mc2 = {mc, mc};
;         f32x2 ps2 = {0.f, 0.f};
; #pragma unroll
;         for (int kb = 0; kb < 2; ++kb)
; #pragma unroll
;           for (int i = 0; i < 16; i += 2) {
;             const f32x2 sv = {s[qb][kb][i], s[qb][kb][i + 1]};
;             const f32x2 e2 = sv * c2 + mc2;
;             f32x2 pv = {fexp2(e2[0]), fexp2(e2[1])};
;             if constexpr (MODE == 1 || MODE == 2) {
;               pv[0] = (sv[0] > -1e29f) ? pv[0] : 0.f;
;               pv[1] = (sv[1] > -1e29f) ? pv[1] : 0.f;
;             }
;             s[qb][kb][i] = pv[0];
;             s[qb][kb][i + 1] = pv[1];
;             ps2 += pv;
;           }
;         lsum[qb] += ps2[0] + ps2[1];
;       }
; #pragma unroll
;       for (int qb = 0; qb < QB; ++qb)
; #pragma unroll
;         for (int kb = 0; kb < 2; ++kb)
; #pragma unroll
;           for (int st = 0; st < 2; ++st) {
;             u32x4 pk;
;             pk[0] = pack2(s[qb][kb][8 * st + 0], s[qb][kb][8 * st + 1]);
;             pk[1] = pack2(s[qb][kb][8 * st + 2], s[qb][kb][8 * st + 3]);
;             pk[2] = pack2(s[qb][kb][8 * st + 4], s[qb][kb][8 * st + 5]);
;             pk[3] = pack2(s[qb][kb][8 * st + 6], s[qb][kb][8 * st + 7]);
;             const bf16x8 pf = __builtin_bit_cast(bf16x8, pk);
;             const unsigned char* vrow = Vb + (kb * 32 + 16 * st + 4 * h + vq) * VST + (16 * vblk + 4 * vp) * 2;
; #pragma unroll
;             for (int d = 0; d < NDB; ++d) {
;               s16x4 lo = __builtin_amdgcn_ds_read_tr16_b64_v4i16((s16x4 __attribute__((address_space(3)))*)(vrow + d * 64));
;               s16x4 hi = __builtin_amdgcn_ds_read_tr16_b64_v4i16((s16x4 __attribute__((address_space(3)))*)(vrow + 8 * VST + d * 64));
;               const bf16x8 vf = __builtin_shufflevector(lo, hi, 0, 1, 2, 3, 4, 5, 6, 7);
;               o[qb][d] = MFMA32(vf, pf, o[qb][d]);
;             }
;           }
.LBB0_823:
	v_max_f32_e32 v98, s17, v193
	v_mul_f32_e32 v98, 0xbe38aa3b, v98
	v_pk_fma_f32 v[80:81], v[8:9], s[16:17], v[98:99] op_sel_hi:[1,0,0]
	v_exp_f32_e32 v8, v80
	v_exp_f32_e32 v9, v81
	v_pk_fma_f32 v[82:83], v[128:129], s[16:17], v[98:99] op_sel_hi:[1,0,0]
	v_pk_fma_f32 v[86:87], v[198:199], s[16:17], v[98:99] op_sel_hi:[1,0,0]
	v_exp_f32_e32 v208, v82
	v_pk_fma_f32 v[94:95], v[132:133], s[16:17], v[98:99] op_sel_hi:[1,0,0]
	v_exp_f32_e32 v209, v83
	v_pk_fma_f32 v[82:83], v[130:131], s[16:17], v[98:99] op_sel_hi:[1,0,0]
	v_pk_add_f32 v[80:81], v[8:9], 0 op_sel_hi:[1,0]
	v_exp_f32_e32 v210, v82
	s_nop 0
	v_exp_f32_e32 v211, v83
	v_pk_fma_f32 v[82:83], v[206:207], s[16:17], v[98:99] op_sel_hi:[1,0,0]
	v_pk_add_f32 v[80:81], v[208:209], v[80:81]
	v_exp_f32_e32 v206, v82
	s_nop 0
	v_exp_f32_e32 v207, v83
	v_pk_add_f32 v[80:81], v[210:211], v[80:81]
	s_nop 0
	s_nop 1
	v_pk_add_f32 v[82:83], v[206:207], v[80:81]
	v_pk_fma_f32 v[80:81], v[204:205], s[16:17], v[98:99] op_sel_hi:[1,0,0]
	v_exp_f32_e32 v80, v80
	v_exp_f32_e32 v81, v81
	s_nop 1
	v_pk_add_f32 v[84:85], v[80:81], v[82:83]
	v_pk_fma_f32 v[82:83], v[202:203], s[16:17], v[98:99] op_sel_hi:[1,0,0]
	v_exp_f32_e32 v82, v82
	v_exp_f32_e32 v83, v83
	v_exp_f32_e32 v90, v86
	s_nop 0
	v_exp_f32_e32 v91, v87
	v_pk_fma_f32 v[86:87], v[134:135], s[16:17], v[98:99] op_sel_hi:[1,0,0]
	v_pk_add_f32 v[84:85], v[82:83], v[84:85]
	v_exp_f32_e32 v134, v86
	s_nop 0
	v_exp_f32_e32 v135, v87
	v_pk_add_f32 v[84:85], v[90:91], v[84:85]
	s_nop 0
	s_nop 1
	v_pk_add_f32 v[86:87], v[134:135], v[84:85]
	v_pk_fma_f32 v[84:85], v[142:143], s[16:17], v[98:99] op_sel_hi:[1,0,0]
	v_exp_f32_e32 v84, v84
	v_exp_f32_e32 v85, v85
	s_nop 1
	v_pk_add_f32 v[88:89], v[84:85], v[86:87]
	v_pk_fma_f32 v[86:87], v[140:141], s[16:17], v[98:99] op_sel_hi:[1,0,0]
	v_exp_f32_e32 v86, v86
	v_exp_f32_e32 v87, v87
	s_nop 1
	v_pk_add_f32 v[92:93], v[86:87], v[88:89]
	v_pk_fma_f32 v[88:89], v[138:139], s[16:17], v[98:99] op_sel_hi:[1,0,0]
	v_exp_f32_e32 v88, v88
	v_exp_f32_e32 v89, v89
	v_cvt_pk_bf16_f32 v138, v90, v91
	v_exp_f32_e32 v132, v94
	v_cvt_pk_bf16_f32 v139, v134, v135
	v_exp_f32_e32 v133, v95
	v_pk_add_f32 v[92:93], v[88:89], v[92:93]
	v_cvt_pk_bf16_f32 v134, v84, v85
	v_cvt_pk_bf16_f32 v135, v86, v87
	s_nop 0
	v_pk_add_f32 v[94:95], v[132:133], v[92:93]
	v_pk_fma_f32 v[92:93], v[136:137], s[16:17], v[98:99] op_sel_hi:[1,0,0]
	v_exp_f32_e32 v92, v92
	v_exp_f32_e32 v93, v93
	v_cvt_pk_bf16_f32 v136, v80, v81
	v_cvt_pk_bf16_f32 v137, v82, v83
	s_nop 0
	v_pk_add_f32 v[96:97], v[92:93], v[94:95]
	v_pk_fma_f32 v[94:95], v[116:117], s[16:17], v[98:99] op_sel_hi:[1,0,0]
	v_exp_f32_e32 v94, v94
	v_exp_f32_e32 v95, v95
	s_nop 1
	v_pk_add_f32 v[100:101], v[94:95], v[96:97]
	v_pk_fma_f32 v[96:97], v[112:113], s[16:17], v[98:99] op_sel_hi:[1,0,0]
	v_exp_f32_e32 v96, v96
	v_exp_f32_e32 v97, v97
	v_pk_fma_f32 v[98:99], v[14:15], s[16:17], v[98:99] op_sel_hi:[1,0,0]
	v_exp_f32_e32 v98, v98
	s_nop 0
	v_exp_f32_e32 v99, v99
	v_pk_add_f32 v[100:101], v[96:97], v[100:101]
	s_nop 0
	s_nop 1
	v_pk_add_f32 v[14:15], v[98:99], v[100:101]
	v_add_f32_e32 v1, v14, v15
	v_max_f32_e32 v14, s17, v192
	v_mul_f32_e32 v14, 0xbe38aa3b, v14
	v_pk_fma_f32 v[100:101], v[200:201], s[16:17], v[14:15] op_sel_hi:[1,0,0]
	v_add_f32_e32 v214, v214, v1
	v_exp_f32_e32 v100, v100
	v_exp_f32_e32 v101, v101
	v_pk_fma_f32 v[106:107], v[196:197], s[16:17], v[14:15] op_sel_hi:[1,0,0]
	v_pk_fma_f32 v[112:113], v[194:195], s[16:17], v[14:15] op_sel_hi:[1,0,0]
	v_exp_f32_e32 v106, v106
	s_nop 0
	v_exp_f32_e32 v107, v107
	v_pk_add_f32 v[110:111], v[100:101], 0 op_sel_hi:[1,0]
	s_nop 0
	v_exp_f32_e32 v116, v112
	s_nop 0
	v_exp_f32_e32 v117, v113
	v_pk_fma_f32 v[112:113], v[126:127], s[16:17], v[14:15] op_sel_hi:[1,0,0]
	v_pk_add_f32 v[110:111], v[106:107], v[110:111]
	v_exp_f32_e32 v126, v112
	s_nop 0
	v_exp_f32_e32 v127, v113
	v_pk_add_f32 v[110:111], v[116:117], v[110:111]
	s_nop 0
	s_nop 1
	v_pk_add_f32 v[112:113], v[126:127], v[110:111]
	v_pk_fma_f32 v[110:111], v[124:125], s[16:17], v[14:15] op_sel_hi:[1,0,0]
	v_exp_f32_e32 v110, v110
	v_exp_f32_e32 v111, v111
	v_pk_fma_f32 v[124:125], v[120:121], s[16:17], v[14:15] op_sel_hi:[1,0,0]
	s_nop 0
	v_exp_f32_e32 v120, v124
	v_exp_f32_e32 v121, v125
	v_pk_fma_f32 v[124:125], v[122:123], s[16:17], v[14:15] op_sel_hi:[1,0,0]
	v_pk_add_f32 v[112:113], v[110:111], v[112:113]
	v_exp_f32_e32 v128, v124
	s_nop 1
	v_exp_f32_e32 v129, v125
	v_pk_add_f32 v[112:113], v[120:121], v[112:113]
	s_nop 0
	v_pk_fma_f32 v[122:123], v[118:119], s[16:17], v[14:15] op_sel_hi:[1,0,0]
	s_nop 0
	v_exp_f32_e32 v130, v122
	v_exp_f32_e32 v131, v123
	v_pk_add_f32 v[112:113], v[128:129], v[112:113]
	s_nop 0
	v_pk_fma_f32 v[118:119], v[114:115], s[16:17], v[14:15] op_sel_hi:[1,0,0]
	s_nop 0
	v_exp_f32_e32 v114, v118
	v_exp_f32_e32 v115, v119
	v_pk_fma_f32 v[118:119], v[108:109], s[16:17], v[14:15] op_sel_hi:[1,0,0]
	v_pk_add_f32 v[112:113], v[130:131], v[112:113]
	v_exp_f32_e32 v118, v118
	s_nop 0
	v_exp_f32_e32 v119, v119
	v_pk_add_f32 v[112:113], v[114:115], v[112:113]
	s_nop 0
	s_nop 1
	v_pk_add_f32 v[108:109], v[118:119], v[112:113]
	v_pk_fma_f32 v[112:113], v[104:105], s[16:17], v[14:15] op_sel_hi:[1,0,0]
	v_exp_f32_e32 v122, v112
	v_exp_f32_e32 v123, v113
	s_nop 1
	v_pk_add_f32 v[104:105], v[122:123], v[108:109]
	v_pk_fma_f32 v[108:109], v[102:103], s[16:17], v[14:15] op_sel_hi:[1,0,0]
	v_exp_f32_e32 v124, v108
	v_exp_f32_e32 v125, v109
	v_pk_fma_f32 v[102:103], v[12:13], s[16:17], v[14:15] op_sel_hi:[1,0,0]
	s_nop 0
	v_exp_f32_e32 v102, v102
	v_exp_f32_e32 v103, v103
	v_pk_add_f32 v[104:105], v[124:125], v[104:105]
	s_nop 0
	s_nop 1
	v_pk_add_f32 v[12:13], v[102:103], v[104:105]
	v_pk_fma_f32 v[104:105], v[10:11], s[16:17], v[14:15] op_sel_hi:[1,0,0]
	v_exp_f32_e32 v104, v104
	v_exp_f32_e32 v105, v105
	s_nop 1
	v_pk_add_f32 v[10:11], v[104:105], v[12:13]
	v_pk_fma_f32 v[12:13], v[6:7], s[16:17], v[14:15] op_sel_hi:[1,0,0]
	v_exp_f32_e32 v108, v12
	v_exp_f32_e32 v109, v13
	v_cvt_pk_bf16_f32 v12, v8, v9
	v_cvt_pk_bf16_f32 v13, v208, v209
	s_nop 1
	v_pk_add_f32 v[6:7], v[108:109], v[10:11]
	v_pk_fma_f32 v[10:11], v[4:5], s[16:17], v[14:15] op_sel_hi:[1,0,0]
	v_exp_f32_e32 v112, v10
	v_exp_f32_e32 v113, v11
	v_cvt_pk_bf16_f32 v14, v210, v211
	v_cvt_pk_bf16_f32 v15, v206, v207
	s_nop 1
	v_pk_add_f32 v[4:5], v[112:113], v[6:7]
	s_nop 0
	v_add_f32_e32 v1, v4, v5
	v_add_f32_e32 v212, v212, v1
	v_add3_u32 v1, s25, v217, v219
	ds_read_b64_tr_b16 v[8:9], v1 offset:9216
	ds_read_b64_tr_b16 v[10:11], v1 offset:10368
	ds_read_b64_tr_b16 v[4:5], v1 offset:9280
	ds_read_b64_tr_b16 v[6:7], v1 offset:10432
	s_waitcnt lgkmcnt(2)
; #define MFMA32(a, b, c) __builtin_amdgcn_mfma_f32_32x32x16_bf16((a), (b), (c), 0, 0, 0)
; template <int DK, int DV, int MODE, int QB, bool PACK = false>
; DI void attn_item(const AttArgs& a, int q0, int t_lo, int t_hi) {
;     ...
; #pragma unroll
;       for (int qb = 0; qb < QB; ++qb)
; #pragma unroll
;         for (int kb = 0; kb < 2; ++kb)
; #pragma unroll
;           for (int st = 0; st < 2; ++st) {
;             u32x4 pk;
;             pk[0] = pack2(s[qb][kb][8 * st + 0], s[qb][kb][8 * st + 1]);
;             pk[1] = pack2(s[qb][kb][8 * st + 2], s[qb][kb][8 * st + 3]);
;             pk[2] = pack2(s[qb][kb][8 * st + 4], s[qb][kb][8 * st + 5]);
;             pk[3] = pack2(s[qb][kb][8 * st + 6], s[qb][kb][8 * st + 7]);
;             const bf16x8 pf = __builtin_bit_cast(bf16x8, pk);
;             const unsigned char* vrow = Vb + (kb * 32 + 16 * st + 4 * h + vq) * VST + (16 * vblk + 4 * vp) * 2;
; #pragma unroll
;             for (int d = 0; d < NDB; ++d) {
;               s16x4 lo = __builtin_amdgcn_ds_read_tr16_b64_v4i16((s16x4 __attribute__((address_space(3)))*)(vrow + d * 64));
;               s16x4 hi = __builtin_amdgcn_ds_read_tr16_b64_v4i16((s16x4 __attribute__((address_space(3)))*)(vrow + 8 * VST + d * 64));
;               const bf16x8 vf = __builtin_shufflevector(lo, hi, 0, 1, 2, 3, 4, 5, 6, 7);
;               o[qb][d] = MFMA32(vf, pf, o[qb][d]);
;             }
;           }
	v_mfma_f32_32x32x16_bf16 v[64:79], v[8:11], v[12:15], v[64:79]
	ds_read_b64_tr_b16 v[80:81], v1 offset:11520
	ds_read_b64_tr_b16 v[82:83], v1 offset:12672
	s_waitcnt lgkmcnt(2)
	v_mfma_f32_32x32x16_bf16 v[48:63], v[4:7], v[12:15], v[48:63]
	ds_read_b64_tr_b16 v[12:13], v1 offset:11584
	ds_read_b64_tr_b16 v[14:15], v1 offset:12736
	s_waitcnt lgkmcnt(2)
	v_mfma_f32_32x32x16_bf16 v[64:79], v[80:83], v[136:139], v[64:79]
	s_waitcnt lgkmcnt(0)
	v_mfma_f32_32x32x16_bf16 v[48:63], v[12:15], v[136:139], v[48:63]
	v_cvt_pk_bf16_f32 v136, v88, v89
	ds_read_b64_tr_b16 v[88:89], v1 offset:13824
	ds_read_b64_tr_b16 v[90:91], v1 offset:14976
	ds_read_b64_tr_b16 v[84:85], v1 offset:13888
	ds_read_b64_tr_b16 v[86:87], v1 offset:15040
	v_cvt_pk_bf16_f32 v137, v132, v133
	v_cvt_pk_bf16_f32 v132, v92, v93
	v_cvt_pk_bf16_f32 v133, v94, v95
	s_waitcnt lgkmcnt(2)
	v_mfma_f32_32x32x16_bf16 v[64:79], v[88:91], v[134:137], v[64:79]
	s_waitcnt lgkmcnt(0)
	v_mfma_f32_32x32x16_bf16 v[48:63], v[84:87], v[134:137], v[48:63]
	v_cvt_pk_bf16_f32 v134, v96, v97
	v_cvt_pk_bf16_f32 v135, v98, v99
	ds_read_b64_tr_b16 v[96:97], v1 offset:16128
	ds_read_b64_tr_b16 v[98:99], v1 offset:17280
	ds_read_b64_tr_b16 v[92:93], v1 offset:16192
	ds_read_b64_tr_b16 v[94:95], v1 offset:17344
	v_mov_b32_e32 v1, v193
	s_waitcnt lgkmcnt(2)
	v_mfma_f32_32x32x16_bf16 v[64:79], v[96:99], v[132:135], v[64:79]
	s_waitcnt lgkmcnt(0)
	v_mfma_f32_32x32x16_bf16 v[48:63], v[92:95], v[132:135], v[48:63]
	v_cvt_pk_bf16_f32 v132, v100, v101
	v_cvt_pk_bf16_f32 v133, v106, v107
	v_cvt_pk_bf16_f32 v134, v116, v117
	v_cvt_pk_bf16_f32 v135, v126, v127
	s_nop 1
	v_mfma_f32_32x32x16_bf16 v[32:47], v[8:11], v[132:135], v[32:47]
	v_mfma_f32_32x32x16_bf16 v[16:31], v[4:7], v[132:135], v[16:31]
	v_cvt_pk_bf16_f32 v4, v110, v111
	v_cvt_pk_bf16_f32 v5, v120, v121
	v_cvt_pk_bf16_f32 v6, v128, v129
	v_cvt_pk_bf16_f32 v7, v130, v131
	s_nop 1
	v_mfma_f32_32x32x16_bf16 v[32:47], v[80:83], v[4:7], v[32:47]
	v_mfma_f32_32x32x16_bf16 v[16:31], v[12:15], v[4:7], v[16:31]
	v_cvt_pk_bf16_f32 v4, v114, v115
	v_cvt_pk_bf16_f32 v5, v118, v119
	v_cvt_pk_bf16_f32 v6, v122, v123
	v_cvt_pk_bf16_f32 v7, v124, v125
	s_nop 1
	v_mfma_f32_32x32x16_bf16 v[32:47], v[88:91], v[4:7], v[32:47]
	v_mfma_f32_32x32x16_bf16 v[16:31], v[84:87], v[4:7], v[16:31]
	v_cvt_pk_bf16_f32 v4, v102, v103
	v_cvt_pk_bf16_f32 v5, v104, v105
	v_cvt_pk_bf16_f32 v6, v108, v109
	v_cvt_pk_bf16_f32 v7, v112, v113
	s_nop 1
	v_mfma_f32_32x32x16_bf16 v[32:47], v[96:99], v[4:7], v[32:47]
	v_mfma_f32_32x32x16_bf16 v[16:31], v[92:95], v[4:7], v[16:31]
